# LN2 dependency wait: only wave 0 of each workgroup polls the 32 completion records, the other waves wait at a workgroup barrier
# speedup vs baseline: 1.0045x; 1.0033x over previous
.LBB0_412:
	s_mul_hi_i32 s13, s70, 0x2aaaaaab
	s_lshr_b32 s14, s13, 31
	s_ashr_i32 s35, s13, 2
	s_add_i32 s35, s35, s14
	s_mul_i32 s13, s35, 24
	s_sub_i32 s60, s70, s13
	s_and_b32 s13, s60, 7
	s_lshl_b32 s13, s13, 10
	v_readlane_b32 s52, v255, 40
	s_add_i32 s52, s52, 0x5d0e2000
	s_lshl_b32 s54, s60, 9
	s_add_u32 s50, s94, 0xcbc9000
	s_addc_u32 s51, s95, 0
	v_and_b32_e32 v226, 31, v137
	v_lshlrev_b32_e32 v226, 4, v226
	v_add_u32_e32 v226, s54, v226
	s_mov_b32 s53, 0x100000
	v_readfirstlane_b32 s54, v137
	s_cmp_lt_u32 s54, 64
	s_cbranch_scc0 .Lln2dep_ok

.Lln2dep_ok:
	s_barrier
	s_lshl_b32 s22, s60, 8
	s_ashr_i32 s23, s22, 31
	s_lshl_b64 s[36:37], s[22:23], 13
	s_or_b32 s36, s36, s13
	s_mov_b32 m0, s8
	v_lshl_add_u64 v[2:3], v[100:101], 0, s[36:37]
	s_mov_b64 s[50:51], 0x10000
	s_lshl_b32 s26, s35, 7
	global_load_lds_dwordx4 v[2:3], off sc1
	v_lshl_add_u64 v[6:7], v[2:3], 0, s[50:51]
	s_add_i32 m0, s8, 0x400
	s_mov_b64 s[52:53], 0x20000
	s_ashr_i32 s27, s26, 31
	global_load_lds_dwordx4 v[6:7], off sc1
	v_lshl_add_u64 v[6:7], v[2:3], 0, s[52:53]
	s_add_i32 m0, s8, 0x800
	s_mov_b64 s[52:53], 0x30000
	s_lshl_b64 s[48:49], s[26:27], 13
	s_or_b32 s48, s48, s13
	global_load_lds_dwordx4 v[6:7], off sc1
	v_lshl_add_u64 v[6:7], v[2:3], 0, s[52:53]
	s_add_i32 m0, s8, 0xc00
	v_lshl_add_u64 v[4:5], v[102:103], 0, s[48:49]
	global_load_lds_dwordx4 v[6:7], off sc1
	s_add_i32 m0, s9, 0x8000
	v_lshl_add_u64 v[6:7], v[4:5], 0, s[50:51]
	global_load_lds_dwordx4 v[4:5], off sc1
	s_add_i32 m0, s9, 0x8400
	s_mov_b64 s[50:51], 0x10080
	global_load_lds_dwordx4 v[6:7], off sc1
	v_lshl_add_u64 v[6:7], v[2:3], 0, s[2:3]
	s_add_i32 m0, s8, 0xc000
	s_mov_b64 s[52:53], 0x20080
	global_load_lds_dwordx4 v[6:7], off sc1
	v_lshl_add_u64 v[6:7], v[2:3], 0, s[50:51]
	s_add_i32 m0, s8, 0xc400
	s_mov_b64 s[54:55], 0x10100
	global_load_lds_dwordx4 v[6:7], off sc1
	v_lshl_add_u64 v[6:7], v[2:3], 0, s[52:53]
	s_add_i32 m0, s8, 0xc800
	s_mov_b64 s[52:53], 0x30080
	global_load_lds_dwordx4 v[6:7], off sc1
	v_lshl_add_u64 v[6:7], v[2:3], 0, s[52:53]
	s_add_i32 m0, s8, 0xcc00
	s_mov_b64 s[52:53], 0x20100
	global_load_lds_dwordx4 v[6:7], off sc1
	v_lshl_add_u64 v[6:7], v[4:5], 0, s[2:3]
	s_add_i32 m0, s9, 0x14000
	v_add_u32_e32 v172, v114, v115
	global_load_lds_dwordx4 v[6:7], off sc1
	v_lshl_add_u64 v[6:7], v[4:5], 0, s[50:51]
	s_add_i32 m0, s9, 0x14400
	s_mov_b64 s[50:51], 0x100
	global_load_lds_dwordx4 v[6:7], off sc1
	v_lshl_add_u64 v[6:7], v[2:3], 0, s[50:51]
	s_add_i32 m0, s8, 0x18000
	v_add_u32_e32 v173, v116, v115
	global_load_lds_dwordx4 v[6:7], off sc1
	v_lshl_add_u64 v[6:7], v[2:3], 0, s[54:55]
	s_add_i32 m0, s8, 0x18400
	v_mov_b32_e32 v38, 0
	global_load_lds_dwordx4 v[6:7], off sc1
	v_lshl_add_u64 v[6:7], v[2:3], 0, s[52:53]
	s_add_i32 m0, s8, 0x18800
	s_mov_b64 s[52:53], 0x30100
	global_load_lds_dwordx4 v[6:7], off sc1
	v_lshl_add_u64 v[2:3], v[2:3], 0, s[52:53]
	s_add_i32 m0, s8, 0x18c00
	v_lshl_add_u64 v[108:109], v[104:105], 0, s[36:37]
	global_load_lds_dwordx4 v[2:3], off sc1
	v_lshl_add_u64 v[2:3], v[4:5], 0, s[50:51]
	s_add_i32 m0, s9, 0x20000
	v_lshl_add_u64 v[110:111], v[106:107], 0, s[48:49]
	global_load_lds_dwordx4 v[2:3], off sc1
	v_lshl_add_u64 v[2:3], v[4:5], 0, s[54:55]
	s_add_i32 m0, s9, 0x20400
	s_lshr_b32 s55, s13, 7
	s_sub_i32 s55, 61, s55
	s_mov_b32 s13, -1
	global_load_lds_dwordx4 v[2:3], off sc1
	s_waitcnt vmcnt(12)
	s_waitcnt lgkmcnt(0)
	s_barrier
	ds_read_b128 v[30:33], v172
	ds_read_b128 v[26:29], v173 offset:2048
	s_waitcnt vmcnt(0)
	ds_read_b128 v[14:17], v173 offset:4096
	ds_read_b128 v[2:5], v173 offset:6144
	ds_read_b128 v[22:25], v161 offset:32768
	ds_read_b128 v[18:21], v164 offset:34816
	ds_read_b128 v[10:13], v164 offset:36864
	ds_read_b128 v[6:9], v164 offset:38912
	s_mov_b32 s14, 0
	s_mov_b32 s19, 1
	s_mov_b32 s23, 0
	v_mov_b32_e32 v39, v38
	v_mov_b32_e32 v40, v38
	v_mov_b32_e32 v41, v38
	v_mov_b32_e32 v42, v38
	v_mov_b32_e32 v43, v38
	v_mov_b32_e32 v44, v38
	v_mov_b32_e32 v45, v38
	v_mov_b32_e32 v46, v38
	v_mov_b32_e32 v47, v38
	v_mov_b32_e32 v48, v38
	v_mov_b32_e32 v49, v38
	v_mov_b32_e32 v50, v38
	v_mov_b32_e32 v51, v38
	v_mov_b32_e32 v52, v38
	v_mov_b32_e32 v53, v38
	v_mov_b32_e32 v54, v38
	v_mov_b32_e32 v55, v38
	v_mov_b32_e32 v56, v38
	v_mov_b32_e32 v57, v38
	v_mov_b32_e32 v58, v38
	v_mov_b32_e32 v59, v38
	v_mov_b32_e32 v60, v38
	v_mov_b32_e32 v61, v38
	v_mov_b32_e32 v62, v38
	v_mov_b32_e32 v63, v38
	v_mov_b32_e32 v64, v38
	v_mov_b32_e32 v65, v38
	v_mov_b32_e32 v66, v38
	v_mov_b32_e32 v67, v38
	v_mov_b32_e32 v68, v38
	v_mov_b32_e32 v69, v38
	v_mov_b32_e32 v78, v38
	v_mov_b32_e32 v79, v38
	v_mov_b32_e32 v80, v38
	v_mov_b32_e32 v81, v38
	v_mov_b32_e32 v70, v38
	v_mov_b32_e32 v71, v38
	v_mov_b32_e32 v72, v38
	v_mov_b32_e32 v73, v38
	v_mov_b32_e32 v74, v38
	v_mov_b32_e32 v75, v38
	v_mov_b32_e32 v76, v38
	v_mov_b32_e32 v77, v38
	v_mov_b32_e32 v34, v38
	v_mov_b32_e32 v35, v38
	v_mov_b32_e32 v36, v38
	v_mov_b32_e32 v37, v38
	v_mov_b32_e32 v86, v38
	v_mov_b32_e32 v87, v38
	v_mov_b32_e32 v88, v38
	v_mov_b32_e32 v89, v38
	v_mov_b32_e32 v94, v38
	v_mov_b32_e32 v95, v38
	v_mov_b32_e32 v96, v38
	v_mov_b32_e32 v97, v38
	v_mov_b32_e32 v90, v38
	v_mov_b32_e32 v91, v38
	v_mov_b32_e32 v92, v38
	v_mov_b32_e32 v93, v38
	v_mov_b32_e32 v82, v38
	v_mov_b32_e32 v83, v38
	v_mov_b32_e32 v84, v38
	v_mov_b32_e32 v85, v38
